# ffn_in: single-buffered A split into two half-tile DMAs, each issued as soon as its fragments (both k-halves) are in registers; B frags of both k-halves held; one vOff register with SGPR base stepping
# baseline (speedup 1.0000x reference)
.Lf2_setup:
	v_and_b32_e32 v70, 7, v196
	v_bfe_u32 v71, v196, 4, 2
	v_bfe_u32 v72, v196, 6, 1
	v_lshl_or_b32 v73, v72, 2, v71
	v_xor_b32_e32 v70, v70, v73
	v_lshrrev_b32_e32 v73, 3, v196
	v_lshlrev_b32_e32 v73, 11, v73
	v_lshl_or_b32 v199, v70, 4, v73
	v_and_b32_e32 v70, 15, v196
	v_bfe_u32 v73, v196, 1, 3
	v_xor_b32_e32 v73, v71, v73
	v_lshlrev_b32_e32 v73, 4, v73
	v_xor_b32_e32 v82, 64, v73
	v_lshlrev_b32_e32 v70, 7, v70
	v_lshrrev_b32_e32 v83, 7, v196
	v_lshl_or_b32 v83, v83, 13, v70
	v_lshl_or_b32 v84, v72, 13, v70
	v_add_u32_e32 v80, v83, v73
	v_add_u32_e32 v81, v83, v82
	v_add_u32_e32 v144, v84, v73
	v_add_u32_e32 v145, v84, v82
	v_readfirstlane_b32 s64, v196
	s_lshr_b32 s64, s64, 6
	s_lshl_b32 s64, s64, 10
	s_cmp_eq_u32 s39, 2
	s_cbranch_scc1 .Lf2_loop
	s_lshl_b32 s30, s8, 18
	s_add_u32 s50, s6, s30
	s_addc_u32 s51, s7, 0
	s_lshl_b32 s30, s49, 18
	s_add_u32 s52, s6, s30
	s_addc_u32 s53, s7, 0
	s_lshl_b32 s30, s21, 18
	s_add_u32 s58, s19, s30
	s_addc_u32 s59, s20, 0
	s_barrier
	s_add_i32 m0, s64, 0x0
	s_nop 0
	global_load_lds_dwordx4 v199, s[50:51]
	s_add_u32 s50, s50, 0x10000
	s_addc_u32 s51, s51, 0
	s_add_i32 m0, s64, 0x1000
	s_nop 0
	global_load_lds_dwordx4 v199, s[50:51]
	s_add_u32 s50, s50, 0x10000
	s_addc_u32 s51, s51, 0
	s_add_i32 m0, s64, 0x2000
	s_nop 0
	global_load_lds_dwordx4 v199, s[50:51]
	s_add_u32 s50, s50, 0x10000
	s_addc_u32 s51, s51, 0
	s_add_i32 m0, s64, 0x3000
	s_nop 0
	global_load_lds_dwordx4 v199, s[50:51]
	s_sub_u32 s50, s50, 0x2ff80
	s_subb_u32 s51, s51, 0
	s_add_i32 m0, s64, 0x4000
	s_nop 0
	global_load_lds_dwordx4 v199, s[52:53]
	s_add_u32 s52, s52, 0x10000
	s_addc_u32 s53, s53, 0
	s_add_i32 m0, s64, 0x5000
	s_nop 0
	global_load_lds_dwordx4 v199, s[52:53]
	s_add_u32 s52, s52, 0x10000
	s_addc_u32 s53, s53, 0
	s_add_i32 m0, s64, 0x6000
	s_nop 0
	global_load_lds_dwordx4 v199, s[52:53]
	s_add_u32 s52, s52, 0x10000
	s_addc_u32 s53, s53, 0
	s_add_i32 m0, s64, 0x7000
	s_nop 0
	global_load_lds_dwordx4 v199, s[52:53]
	s_sub_u32 s52, s52, 0x2ff80
	s_subb_u32 s53, s53, 0
	s_add_i32 m0, s64, 0x8000
	s_nop 0
	global_load_lds_dwordx4 v199, s[58:59]
	s_add_u32 s58, s58, 0x10000
	s_addc_u32 s59, s59, 0
	s_add_i32 m0, s64, 0x9000
	s_nop 0
	global_load_lds_dwordx4 v199, s[58:59]
	s_add_u32 s58, s58, 0x10000
	s_addc_u32 s59, s59, 0
	s_add_i32 m0, s64, 0xa000
	s_nop 0
	global_load_lds_dwordx4 v199, s[58:59]
	s_add_u32 s58, s58, 0x10000
	s_addc_u32 s59, s59, 0
	s_add_i32 m0, s64, 0xb000
	s_nop 0
	global_load_lds_dwordx4 v199, s[58:59]
	s_sub_u32 s58, s58, 0x2ff80
	s_subb_u32 s59, s59, 0

.Lf2_k:
	s_waitcnt vmcnt(0)
	s_barrier
	s_add_i32 m0, s64, 0xc000
	s_nop 0
	global_load_lds_dwordx4 v199, s[58:59]
	s_add_u32 s58, s58, 0x10000
	s_addc_u32 s59, s59, 0
	s_add_i32 m0, s64, 0xd000
	s_nop 0
	global_load_lds_dwordx4 v199, s[58:59]
	s_add_u32 s58, s58, 0x10000
	s_addc_u32 s59, s59, 0
	s_add_i32 m0, s64, 0xe000
	s_nop 0
	global_load_lds_dwordx4 v199, s[58:59]
	s_add_u32 s58, s58, 0x10000
	s_addc_u32 s59, s59, 0
	s_add_i32 m0, s64, 0xf000
	s_nop 0
	global_load_lds_dwordx4 v199, s[58:59]
	s_sub_u32 s58, s58, 0x2ff80
	s_subb_u32 s59, s59, 0
	ds_read_b128 v[148:151], v80 offset:0
	ds_read_b128 v[152:155], v80 offset:2048
	ds_read_b128 v[156:159], v80 offset:4096
	ds_read_b128 v[160:163], v80 offset:6144
	ds_read_b128 v[164:167], v81 offset:0
	ds_read_b128 v[168:171], v81 offset:2048
	ds_read_b128 v[174:177], v81 offset:4096
	ds_read_b128 v[182:185], v81 offset:6144
	ds_read_b128 v[188:191], v144 offset:32768
	ds_read_b128 v[192:195], v144 offset:34816
	ds_read_b128 v[208:211], v144 offset:36864
	ds_read_b128 v[212:215], v144 offset:38912
	ds_read_b128 v[216:219], v145 offset:32768
	ds_read_b128 v[220:223], v145 offset:34816
	ds_read_b128 v[242:245], v145 offset:36864
	ds_read_b128 v[76:79], v145 offset:38912
	s_waitcnt lgkmcnt(8)
	s_barrier
	s_add_i32 m0, s64, 0x0
	s_nop 0
	global_load_lds_dwordx4 v199, s[50:51]
	s_add_u32 s50, s50, 0x10000
	s_addc_u32 s51, s51, 0
	s_add_i32 m0, s64, 0x1000
	s_nop 0
	global_load_lds_dwordx4 v199, s[50:51]
	s_add_u32 s50, s50, 0x10000
	s_addc_u32 s51, s51, 0
	s_add_i32 m0, s64, 0x2000
	s_nop 0
	global_load_lds_dwordx4 v199, s[50:51]
	s_add_u32 s50, s50, 0x10000
	s_addc_u32 s51, s51, 0
	s_add_i32 m0, s64, 0x3000
	s_nop 0
	global_load_lds_dwordx4 v199, s[50:51]
	s_sub_u32 s50, s50, 0x2ff80
	s_subb_u32 s51, s51, 0
	s_setprio 1
	s_waitcnt lgkmcnt(4)
	v_mfma_f32_16x16x32_bf16 v[62:65], v[188:191], v[148:151], v[62:65]
	v_mfma_f32_16x16x32_bf16 v[54:57], v[192:195], v[148:151], v[54:57]
	v_mfma_f32_16x16x32_bf16 v[58:61], v[208:211], v[148:151], v[58:61]
	v_mfma_f32_16x16x32_bf16 v[50:53], v[212:215], v[148:151], v[50:53]
	v_mfma_f32_16x16x32_bf16 v[46:49], v[188:191], v[152:155], v[46:49]
	v_mfma_f32_16x16x32_bf16 v[38:41], v[192:195], v[152:155], v[38:41]
	v_mfma_f32_16x16x32_bf16 v[42:45], v[208:211], v[152:155], v[42:45]
	v_mfma_f32_16x16x32_bf16 v[34:37], v[212:215], v[152:155], v[34:37]
	v_mfma_f32_16x16x32_bf16 v[30:33], v[188:191], v[156:159], v[30:33]
	v_mfma_f32_16x16x32_bf16 v[22:25], v[192:195], v[156:159], v[22:25]
	v_mfma_f32_16x16x32_bf16 v[26:29], v[208:211], v[156:159], v[26:29]
	v_mfma_f32_16x16x32_bf16 v[18:21], v[212:215], v[156:159], v[18:21]
	v_mfma_f32_16x16x32_bf16 v[14:17], v[188:191], v[160:163], v[14:17]
	v_mfma_f32_16x16x32_bf16 v[6:9], v[192:195], v[160:163], v[6:9]
	v_mfma_f32_16x16x32_bf16 v[10:13], v[208:211], v[160:163], v[10:13]
	v_mfma_f32_16x16x32_bf16 v[2:5], v[212:215], v[160:163], v[2:5]
	s_waitcnt lgkmcnt(0)
	v_mfma_f32_16x16x32_bf16 v[62:65], v[216:219], v[164:167], v[62:65]
	v_mfma_f32_16x16x32_bf16 v[54:57], v[220:223], v[164:167], v[54:57]
	v_mfma_f32_16x16x32_bf16 v[58:61], v[242:245], v[164:167], v[58:61]
	v_mfma_f32_16x16x32_bf16 v[50:53], v[76:79], v[164:167], v[50:53]
	v_mfma_f32_16x16x32_bf16 v[46:49], v[216:219], v[168:171], v[46:49]
	v_mfma_f32_16x16x32_bf16 v[38:41], v[220:223], v[168:171], v[38:41]
	v_mfma_f32_16x16x32_bf16 v[42:45], v[242:245], v[168:171], v[42:45]
	v_mfma_f32_16x16x32_bf16 v[34:37], v[76:79], v[168:171], v[34:37]
	v_mfma_f32_16x16x32_bf16 v[30:33], v[216:219], v[174:177], v[30:33]
	v_mfma_f32_16x16x32_bf16 v[22:25], v[220:223], v[174:177], v[22:25]
	v_mfma_f32_16x16x32_bf16 v[26:29], v[242:245], v[174:177], v[26:29]
	v_mfma_f32_16x16x32_bf16 v[18:21], v[76:79], v[174:177], v[18:21]
	v_mfma_f32_16x16x32_bf16 v[14:17], v[216:219], v[182:185], v[14:17]
	v_mfma_f32_16x16x32_bf16 v[6:9], v[220:223], v[182:185], v[6:9]
	v_mfma_f32_16x16x32_bf16 v[10:13], v[242:245], v[182:185], v[10:13]
	v_mfma_f32_16x16x32_bf16 v[2:5], v[76:79], v[182:185], v[2:5]
	s_setprio 0
	ds_read_b128 v[148:151], v80 offset:16384
	ds_read_b128 v[152:155], v80 offset:18432
	ds_read_b128 v[156:159], v80 offset:20480
	ds_read_b128 v[160:163], v80 offset:22528
	ds_read_b128 v[164:167], v81 offset:16384
	ds_read_b128 v[168:171], v81 offset:18432
	ds_read_b128 v[174:177], v81 offset:20480
	ds_read_b128 v[182:185], v81 offset:22528
	s_waitcnt lgkmcnt(0)
	s_barrier
	s_add_i32 m0, s64, 0x4000
	s_nop 0
	global_load_lds_dwordx4 v199, s[52:53]
	s_add_u32 s52, s52, 0x10000
	s_addc_u32 s53, s53, 0
	s_add_i32 m0, s64, 0x5000
	s_nop 0
	global_load_lds_dwordx4 v199, s[52:53]
	s_add_u32 s52, s52, 0x10000
	s_addc_u32 s53, s53, 0
	s_add_i32 m0, s64, 0x6000
	s_nop 0
	global_load_lds_dwordx4 v199, s[52:53]
	s_add_u32 s52, s52, 0x10000
	s_addc_u32 s53, s53, 0
	s_add_i32 m0, s64, 0x7000
	s_nop 0
	global_load_lds_dwordx4 v199, s[52:53]
	s_sub_u32 s52, s52, 0x2ff80
	s_subb_u32 s53, s53, 0
	s_setprio 1
	s_waitcnt lgkmcnt(4)
	v_mfma_f32_16x16x32_bf16 v[66:69], v[188:191], v[148:151], v[66:69]
	v_mfma_f32_16x16x32_bf16 v[70:73], v[192:195], v[148:151], v[70:73]
	v_mfma_f32_16x16x32_bf16 v[82:85], v[208:211], v[148:151], v[82:85]
	v_mfma_f32_16x16x32_bf16 v[86:89], v[212:215], v[148:151], v[86:89]
	v_mfma_f32_16x16x32_bf16 v[90:93], v[188:191], v[152:155], v[90:93]
	v_mfma_f32_16x16x32_bf16 v[94:97], v[192:195], v[152:155], v[94:97]
	v_mfma_f32_16x16x32_bf16 v[98:101], v[208:211], v[152:155], v[98:101]
	v_mfma_f32_16x16x32_bf16 v[102:105], v[212:215], v[152:155], v[102:105]
	v_mfma_f32_16x16x32_bf16 v[106:109], v[188:191], v[156:159], v[106:109]
	v_mfma_f32_16x16x32_bf16 v[110:113], v[192:195], v[156:159], v[110:113]
	v_mfma_f32_16x16x32_bf16 v[114:117], v[208:211], v[156:159], v[114:117]
	v_mfma_f32_16x16x32_bf16 v[118:121], v[212:215], v[156:159], v[118:121]
	v_mfma_f32_16x16x32_bf16 v[122:125], v[188:191], v[160:163], v[122:125]
	v_mfma_f32_16x16x32_bf16 v[126:129], v[192:195], v[160:163], v[126:129]
	v_mfma_f32_16x16x32_bf16 v[136:139], v[208:211], v[160:163], v[136:139]
	v_mfma_f32_16x16x32_bf16 v[140:143], v[212:215], v[160:163], v[140:143]
	s_waitcnt lgkmcnt(0)
	v_mfma_f32_16x16x32_bf16 v[66:69], v[216:219], v[164:167], v[66:69]
	v_mfma_f32_16x16x32_bf16 v[70:73], v[220:223], v[164:167], v[70:73]
	v_mfma_f32_16x16x32_bf16 v[82:85], v[242:245], v[164:167], v[82:85]
	v_mfma_f32_16x16x32_bf16 v[86:89], v[76:79], v[164:167], v[86:89]
	v_mfma_f32_16x16x32_bf16 v[90:93], v[216:219], v[168:171], v[90:93]
	v_mfma_f32_16x16x32_bf16 v[94:97], v[220:223], v[168:171], v[94:97]
	v_mfma_f32_16x16x32_bf16 v[98:101], v[242:245], v[168:171], v[98:101]
	v_mfma_f32_16x16x32_bf16 v[102:105], v[76:79], v[168:171], v[102:105]
	v_mfma_f32_16x16x32_bf16 v[106:109], v[216:219], v[174:177], v[106:109]
	v_mfma_f32_16x16x32_bf16 v[110:113], v[220:223], v[174:177], v[110:113]
	v_mfma_f32_16x16x32_bf16 v[114:117], v[242:245], v[174:177], v[114:117]
	v_mfma_f32_16x16x32_bf16 v[118:121], v[76:79], v[174:177], v[118:121]
	v_mfma_f32_16x16x32_bf16 v[122:125], v[216:219], v[182:185], v[122:125]
	v_mfma_f32_16x16x32_bf16 v[126:129], v[220:223], v[182:185], v[126:129]
	v_mfma_f32_16x16x32_bf16 v[136:139], v[242:245], v[182:185], v[136:139]
	v_mfma_f32_16x16x32_bf16 v[140:143], v[76:79], v[182:185], v[140:143]
	s_setprio 0
	s_waitcnt vmcnt(0)
	s_barrier
	s_add_i32 m0, s64, 0x8000
	s_nop 0
	global_load_lds_dwordx4 v199, s[58:59]
	s_add_u32 s58, s58, 0x10000
	s_addc_u32 s59, s59, 0
	s_add_i32 m0, s64, 0x9000
	s_nop 0
	global_load_lds_dwordx4 v199, s[58:59]
	s_add_u32 s58, s58, 0x10000
	s_addc_u32 s59, s59, 0
	s_add_i32 m0, s64, 0xa000
	s_nop 0
	global_load_lds_dwordx4 v199, s[58:59]
	s_add_u32 s58, s58, 0x10000
	s_addc_u32 s59, s59, 0
	s_add_i32 m0, s64, 0xb000
	s_nop 0
	global_load_lds_dwordx4 v199, s[58:59]
	s_sub_u32 s58, s58, 0x2ff80
	s_subb_u32 s59, s59, 0
	ds_read_b128 v[148:151], v80 offset:0
	ds_read_b128 v[152:155], v80 offset:2048
	ds_read_b128 v[156:159], v80 offset:4096
	ds_read_b128 v[160:163], v80 offset:6144
	ds_read_b128 v[164:167], v81 offset:0
	ds_read_b128 v[168:171], v81 offset:2048
	ds_read_b128 v[174:177], v81 offset:4096
	ds_read_b128 v[182:185], v81 offset:6144
	ds_read_b128 v[188:191], v144 offset:49152
	ds_read_b128 v[192:195], v144 offset:51200
	ds_read_b128 v[208:211], v144 offset:53248
	ds_read_b128 v[212:215], v144 offset:55296
	ds_read_b128 v[216:219], v145 offset:49152
	ds_read_b128 v[220:223], v145 offset:51200
	ds_read_b128 v[242:245], v145 offset:53248
	ds_read_b128 v[76:79], v145 offset:55296
	s_waitcnt lgkmcnt(8)
	s_barrier
	s_add_i32 m0, s64, 0x0
	s_nop 0
	global_load_lds_dwordx4 v199, s[50:51]
	s_add_u32 s50, s50, 0x10000
	s_addc_u32 s51, s51, 0
	s_add_i32 m0, s64, 0x1000
	s_nop 0
	global_load_lds_dwordx4 v199, s[50:51]
	s_add_u32 s50, s50, 0x10000
	s_addc_u32 s51, s51, 0
	s_add_i32 m0, s64, 0x2000
	s_nop 0
	global_load_lds_dwordx4 v199, s[50:51]
	s_add_u32 s50, s50, 0x10000
	s_addc_u32 s51, s51, 0
	s_add_i32 m0, s64, 0x3000
	s_nop 0
	global_load_lds_dwordx4 v199, s[50:51]
	s_sub_u32 s50, s50, 0x2ff80
	s_subb_u32 s51, s51, 0
	s_setprio 1
	s_waitcnt lgkmcnt(4)
	v_mfma_f32_16x16x32_bf16 v[62:65], v[188:191], v[148:151], v[62:65]
	v_mfma_f32_16x16x32_bf16 v[54:57], v[192:195], v[148:151], v[54:57]
	v_mfma_f32_16x16x32_bf16 v[58:61], v[208:211], v[148:151], v[58:61]
	v_mfma_f32_16x16x32_bf16 v[50:53], v[212:215], v[148:151], v[50:53]
	v_mfma_f32_16x16x32_bf16 v[46:49], v[188:191], v[152:155], v[46:49]
	v_mfma_f32_16x16x32_bf16 v[38:41], v[192:195], v[152:155], v[38:41]
	v_mfma_f32_16x16x32_bf16 v[42:45], v[208:211], v[152:155], v[42:45]
	v_mfma_f32_16x16x32_bf16 v[34:37], v[212:215], v[152:155], v[34:37]
	v_mfma_f32_16x16x32_bf16 v[30:33], v[188:191], v[156:159], v[30:33]
	v_mfma_f32_16x16x32_bf16 v[22:25], v[192:195], v[156:159], v[22:25]
	v_mfma_f32_16x16x32_bf16 v[26:29], v[208:211], v[156:159], v[26:29]
	v_mfma_f32_16x16x32_bf16 v[18:21], v[212:215], v[156:159], v[18:21]
	v_mfma_f32_16x16x32_bf16 v[14:17], v[188:191], v[160:163], v[14:17]
	v_mfma_f32_16x16x32_bf16 v[6:9], v[192:195], v[160:163], v[6:9]
	v_mfma_f32_16x16x32_bf16 v[10:13], v[208:211], v[160:163], v[10:13]
	v_mfma_f32_16x16x32_bf16 v[2:5], v[212:215], v[160:163], v[2:5]
	s_waitcnt lgkmcnt(0)
	v_mfma_f32_16x16x32_bf16 v[62:65], v[216:219], v[164:167], v[62:65]
	v_mfma_f32_16x16x32_bf16 v[54:57], v[220:223], v[164:167], v[54:57]
	v_mfma_f32_16x16x32_bf16 v[58:61], v[242:245], v[164:167], v[58:61]
	v_mfma_f32_16x16x32_bf16 v[50:53], v[76:79], v[164:167], v[50:53]
	v_mfma_f32_16x16x32_bf16 v[46:49], v[216:219], v[168:171], v[46:49]
	v_mfma_f32_16x16x32_bf16 v[38:41], v[220:223], v[168:171], v[38:41]
	v_mfma_f32_16x16x32_bf16 v[42:45], v[242:245], v[168:171], v[42:45]
	v_mfma_f32_16x16x32_bf16 v[34:37], v[76:79], v[168:171], v[34:37]
	v_mfma_f32_16x16x32_bf16 v[30:33], v[216:219], v[174:177], v[30:33]
	v_mfma_f32_16x16x32_bf16 v[22:25], v[220:223], v[174:177], v[22:25]
	v_mfma_f32_16x16x32_bf16 v[26:29], v[242:245], v[174:177], v[26:29]
	v_mfma_f32_16x16x32_bf16 v[18:21], v[76:79], v[174:177], v[18:21]
	v_mfma_f32_16x16x32_bf16 v[14:17], v[216:219], v[182:185], v[14:17]
	v_mfma_f32_16x16x32_bf16 v[6:9], v[220:223], v[182:185], v[6:9]
	v_mfma_f32_16x16x32_bf16 v[10:13], v[242:245], v[182:185], v[10:13]
	v_mfma_f32_16x16x32_bf16 v[2:5], v[76:79], v[182:185], v[2:5]
	s_setprio 0
	ds_read_b128 v[148:151], v80 offset:16384
	ds_read_b128 v[152:155], v80 offset:18432
	ds_read_b128 v[156:159], v80 offset:20480
	ds_read_b128 v[160:163], v80 offset:22528
	ds_read_b128 v[164:167], v81 offset:16384
	ds_read_b128 v[168:171], v81 offset:18432
	ds_read_b128 v[174:177], v81 offset:20480
	ds_read_b128 v[182:185], v81 offset:22528
	s_waitcnt lgkmcnt(0)
	s_barrier
	s_add_i32 m0, s64, 0x4000
	s_nop 0
	global_load_lds_dwordx4 v199, s[52:53]
	s_add_u32 s52, s52, 0x10000
	s_addc_u32 s53, s53, 0
	s_add_i32 m0, s64, 0x5000
	s_nop 0
	global_load_lds_dwordx4 v199, s[52:53]
	s_add_u32 s52, s52, 0x10000
	s_addc_u32 s53, s53, 0
	s_add_i32 m0, s64, 0x6000
	s_nop 0
	global_load_lds_dwordx4 v199, s[52:53]
	s_add_u32 s52, s52, 0x10000
	s_addc_u32 s53, s53, 0
	s_add_i32 m0, s64, 0x7000
	s_nop 0
	global_load_lds_dwordx4 v199, s[52:53]
	s_sub_u32 s52, s52, 0x2ff80
	s_subb_u32 s53, s53, 0
	s_setprio 1
	s_waitcnt lgkmcnt(4)
	v_mfma_f32_16x16x32_bf16 v[66:69], v[188:191], v[148:151], v[66:69]
	v_mfma_f32_16x16x32_bf16 v[70:73], v[192:195], v[148:151], v[70:73]
	v_mfma_f32_16x16x32_bf16 v[82:85], v[208:211], v[148:151], v[82:85]
	v_mfma_f32_16x16x32_bf16 v[86:89], v[212:215], v[148:151], v[86:89]
	v_mfma_f32_16x16x32_bf16 v[90:93], v[188:191], v[152:155], v[90:93]
	v_mfma_f32_16x16x32_bf16 v[94:97], v[192:195], v[152:155], v[94:97]
	v_mfma_f32_16x16x32_bf16 v[98:101], v[208:211], v[152:155], v[98:101]
	v_mfma_f32_16x16x32_bf16 v[102:105], v[212:215], v[152:155], v[102:105]
	v_mfma_f32_16x16x32_bf16 v[106:109], v[188:191], v[156:159], v[106:109]
	v_mfma_f32_16x16x32_bf16 v[110:113], v[192:195], v[156:159], v[110:113]
	v_mfma_f32_16x16x32_bf16 v[114:117], v[208:211], v[156:159], v[114:117]
	v_mfma_f32_16x16x32_bf16 v[118:121], v[212:215], v[156:159], v[118:121]
	v_mfma_f32_16x16x32_bf16 v[122:125], v[188:191], v[160:163], v[122:125]
	v_mfma_f32_16x16x32_bf16 v[126:129], v[192:195], v[160:163], v[126:129]
	v_mfma_f32_16x16x32_bf16 v[136:139], v[208:211], v[160:163], v[136:139]
	v_mfma_f32_16x16x32_bf16 v[140:143], v[212:215], v[160:163], v[140:143]
	s_waitcnt lgkmcnt(0)
	v_mfma_f32_16x16x32_bf16 v[66:69], v[216:219], v[164:167], v[66:69]
	v_mfma_f32_16x16x32_bf16 v[70:73], v[220:223], v[164:167], v[70:73]
	v_mfma_f32_16x16x32_bf16 v[82:85], v[242:245], v[164:167], v[82:85]
	v_mfma_f32_16x16x32_bf16 v[86:89], v[76:79], v[164:167], v[86:89]
	v_mfma_f32_16x16x32_bf16 v[90:93], v[216:219], v[168:171], v[90:93]
	v_mfma_f32_16x16x32_bf16 v[94:97], v[220:223], v[168:171], v[94:97]
	v_mfma_f32_16x16x32_bf16 v[98:101], v[242:245], v[168:171], v[98:101]
	v_mfma_f32_16x16x32_bf16 v[102:105], v[76:79], v[168:171], v[102:105]
	v_mfma_f32_16x16x32_bf16 v[106:109], v[216:219], v[174:177], v[106:109]
	v_mfma_f32_16x16x32_bf16 v[110:113], v[220:223], v[174:177], v[110:113]
	v_mfma_f32_16x16x32_bf16 v[114:117], v[242:245], v[174:177], v[114:117]
	v_mfma_f32_16x16x32_bf16 v[118:121], v[76:79], v[174:177], v[118:121]
	v_mfma_f32_16x16x32_bf16 v[122:125], v[216:219], v[182:185], v[122:125]
	v_mfma_f32_16x16x32_bf16 v[126:129], v[220:223], v[182:185], v[126:129]
	v_mfma_f32_16x16x32_bf16 v[136:139], v[242:245], v[182:185], v[136:139]
	v_mfma_f32_16x16x32_bf16 v[140:143], v[76:79], v[182:185], v[140:143]
	s_setprio 0
	s_add_i32 s65, s65, -1
	s_cmp_lg_u32 s65, 0
	s_cbranch_scc1 .Lf2_k
	s_waitcnt vmcnt(0)
	s_barrier
	s_add_i32 m0, s64, 0xc000
	s_nop 0
	global_load_lds_dwordx4 v199, s[58:59]
	s_add_u32 s58, s58, 0x10000
	s_addc_u32 s59, s59, 0
	s_add_i32 m0, s64, 0xd000
	s_nop 0
	global_load_lds_dwordx4 v199, s[58:59]
	s_add_u32 s58, s58, 0x10000
	s_addc_u32 s59, s59, 0
	s_add_i32 m0, s64, 0xe000
	s_nop 0
	global_load_lds_dwordx4 v199, s[58:59]
	s_add_u32 s58, s58, 0x10000
	s_addc_u32 s59, s59, 0
	s_add_i32 m0, s64, 0xf000
	s_nop 0
	global_load_lds_dwordx4 v199, s[58:59]
	s_sub_u32 s58, s58, 0x2ff80
	s_subb_u32 s59, s59, 0
	ds_read_b128 v[148:151], v80 offset:0
	ds_read_b128 v[152:155], v80 offset:2048
	ds_read_b128 v[156:159], v80 offset:4096
	ds_read_b128 v[160:163], v80 offset:6144
	ds_read_b128 v[164:167], v81 offset:0
	ds_read_b128 v[168:171], v81 offset:2048
	ds_read_b128 v[174:177], v81 offset:4096
	ds_read_b128 v[182:185], v81 offset:6144
	ds_read_b128 v[188:191], v144 offset:32768
	ds_read_b128 v[192:195], v144 offset:34816
	ds_read_b128 v[208:211], v144 offset:36864
	ds_read_b128 v[212:215], v144 offset:38912
	ds_read_b128 v[216:219], v145 offset:32768
	ds_read_b128 v[220:223], v145 offset:34816
	ds_read_b128 v[242:245], v145 offset:36864
	ds_read_b128 v[76:79], v145 offset:38912
	s_waitcnt lgkmcnt(8)
	s_barrier
	s_add_i32 m0, s64, 0x0
	s_nop 0
	global_load_lds_dwordx4 v199, s[50:51]
	s_add_u32 s50, s50, 0x10000
	s_addc_u32 s51, s51, 0
	s_add_i32 m0, s64, 0x1000
	s_nop 0
	global_load_lds_dwordx4 v199, s[50:51]
	s_add_u32 s50, s50, 0x10000
	s_addc_u32 s51, s51, 0
	s_add_i32 m0, s64, 0x2000
	s_nop 0
	global_load_lds_dwordx4 v199, s[50:51]
	s_add_u32 s50, s50, 0x10000
	s_addc_u32 s51, s51, 0
	s_add_i32 m0, s64, 0x3000
	s_nop 0
	global_load_lds_dwordx4 v199, s[50:51]
	s_sub_u32 s50, s50, 0x2ff80
	s_subb_u32 s51, s51, 0
	s_setprio 1
	s_waitcnt lgkmcnt(4)
	v_mfma_f32_16x16x32_bf16 v[62:65], v[188:191], v[148:151], v[62:65]
	v_mfma_f32_16x16x32_bf16 v[54:57], v[192:195], v[148:151], v[54:57]
	v_mfma_f32_16x16x32_bf16 v[58:61], v[208:211], v[148:151], v[58:61]
	v_mfma_f32_16x16x32_bf16 v[50:53], v[212:215], v[148:151], v[50:53]
	v_mfma_f32_16x16x32_bf16 v[46:49], v[188:191], v[152:155], v[46:49]
	v_mfma_f32_16x16x32_bf16 v[38:41], v[192:195], v[152:155], v[38:41]
	v_mfma_f32_16x16x32_bf16 v[42:45], v[208:211], v[152:155], v[42:45]
	v_mfma_f32_16x16x32_bf16 v[34:37], v[212:215], v[152:155], v[34:37]
	v_mfma_f32_16x16x32_bf16 v[30:33], v[188:191], v[156:159], v[30:33]
	v_mfma_f32_16x16x32_bf16 v[22:25], v[192:195], v[156:159], v[22:25]
	v_mfma_f32_16x16x32_bf16 v[26:29], v[208:211], v[156:159], v[26:29]
	v_mfma_f32_16x16x32_bf16 v[18:21], v[212:215], v[156:159], v[18:21]
	v_mfma_f32_16x16x32_bf16 v[14:17], v[188:191], v[160:163], v[14:17]
	v_mfma_f32_16x16x32_bf16 v[6:9], v[192:195], v[160:163], v[6:9]
	v_mfma_f32_16x16x32_bf16 v[10:13], v[208:211], v[160:163], v[10:13]
	v_mfma_f32_16x16x32_bf16 v[2:5], v[212:215], v[160:163], v[2:5]
	s_waitcnt lgkmcnt(0)
	v_mfma_f32_16x16x32_bf16 v[62:65], v[216:219], v[164:167], v[62:65]
	v_mfma_f32_16x16x32_bf16 v[54:57], v[220:223], v[164:167], v[54:57]
	v_mfma_f32_16x16x32_bf16 v[58:61], v[242:245], v[164:167], v[58:61]
	v_mfma_f32_16x16x32_bf16 v[50:53], v[76:79], v[164:167], v[50:53]
	v_mfma_f32_16x16x32_bf16 v[46:49], v[216:219], v[168:171], v[46:49]
	v_mfma_f32_16x16x32_bf16 v[38:41], v[220:223], v[168:171], v[38:41]
	v_mfma_f32_16x16x32_bf16 v[42:45], v[242:245], v[168:171], v[42:45]
	v_mfma_f32_16x16x32_bf16 v[34:37], v[76:79], v[168:171], v[34:37]
	v_mfma_f32_16x16x32_bf16 v[30:33], v[216:219], v[174:177], v[30:33]
	v_mfma_f32_16x16x32_bf16 v[22:25], v[220:223], v[174:177], v[22:25]
	v_mfma_f32_16x16x32_bf16 v[26:29], v[242:245], v[174:177], v[26:29]
	v_mfma_f32_16x16x32_bf16 v[18:21], v[76:79], v[174:177], v[18:21]
	v_mfma_f32_16x16x32_bf16 v[14:17], v[216:219], v[182:185], v[14:17]
	v_mfma_f32_16x16x32_bf16 v[6:9], v[220:223], v[182:185], v[6:9]
	v_mfma_f32_16x16x32_bf16 v[10:13], v[242:245], v[182:185], v[10:13]
	v_mfma_f32_16x16x32_bf16 v[2:5], v[76:79], v[182:185], v[2:5]
	s_setprio 0
	ds_read_b128 v[148:151], v80 offset:16384
	ds_read_b128 v[152:155], v80 offset:18432
	ds_read_b128 v[156:159], v80 offset:20480
	ds_read_b128 v[160:163], v80 offset:22528
	ds_read_b128 v[164:167], v81 offset:16384
	ds_read_b128 v[168:171], v81 offset:18432
	ds_read_b128 v[174:177], v81 offset:20480
	ds_read_b128 v[182:185], v81 offset:22528
	s_waitcnt lgkmcnt(0)
	s_barrier
	s_add_i32 m0, s64, 0x4000
	s_nop 0
	global_load_lds_dwordx4 v199, s[52:53]
	s_add_u32 s52, s52, 0x10000
	s_addc_u32 s53, s53, 0
	s_add_i32 m0, s64, 0x5000
	s_nop 0
	global_load_lds_dwordx4 v199, s[52:53]
	s_add_u32 s52, s52, 0x10000
	s_addc_u32 s53, s53, 0
	s_add_i32 m0, s64, 0x6000
	s_nop 0
	global_load_lds_dwordx4 v199, s[52:53]
	s_add_u32 s52, s52, 0x10000
	s_addc_u32 s53, s53, 0
	s_add_i32 m0, s64, 0x7000
	s_nop 0
	global_load_lds_dwordx4 v199, s[52:53]
	s_sub_u32 s52, s52, 0x2ff80
	s_subb_u32 s53, s53, 0
	s_setprio 1
	s_waitcnt lgkmcnt(4)
	v_mfma_f32_16x16x32_bf16 v[66:69], v[188:191], v[148:151], v[66:69]
	v_mfma_f32_16x16x32_bf16 v[70:73], v[192:195], v[148:151], v[70:73]
	v_mfma_f32_16x16x32_bf16 v[82:85], v[208:211], v[148:151], v[82:85]
	v_mfma_f32_16x16x32_bf16 v[86:89], v[212:215], v[148:151], v[86:89]
	v_mfma_f32_16x16x32_bf16 v[90:93], v[188:191], v[152:155], v[90:93]
	v_mfma_f32_16x16x32_bf16 v[94:97], v[192:195], v[152:155], v[94:97]
	v_mfma_f32_16x16x32_bf16 v[98:101], v[208:211], v[152:155], v[98:101]
	v_mfma_f32_16x16x32_bf16 v[102:105], v[212:215], v[152:155], v[102:105]
	v_mfma_f32_16x16x32_bf16 v[106:109], v[188:191], v[156:159], v[106:109]
	v_mfma_f32_16x16x32_bf16 v[110:113], v[192:195], v[156:159], v[110:113]
	v_mfma_f32_16x16x32_bf16 v[114:117], v[208:211], v[156:159], v[114:117]
	v_mfma_f32_16x16x32_bf16 v[118:121], v[212:215], v[156:159], v[118:121]
	v_mfma_f32_16x16x32_bf16 v[122:125], v[188:191], v[160:163], v[122:125]
	v_mfma_f32_16x16x32_bf16 v[126:129], v[192:195], v[160:163], v[126:129]
	v_mfma_f32_16x16x32_bf16 v[136:139], v[208:211], v[160:163], v[136:139]
	v_mfma_f32_16x16x32_bf16 v[140:143], v[212:215], v[160:163], v[140:143]
	s_waitcnt lgkmcnt(0)
	v_mfma_f32_16x16x32_bf16 v[66:69], v[216:219], v[164:167], v[66:69]
	v_mfma_f32_16x16x32_bf16 v[70:73], v[220:223], v[164:167], v[70:73]
	v_mfma_f32_16x16x32_bf16 v[82:85], v[242:245], v[164:167], v[82:85]
	v_mfma_f32_16x16x32_bf16 v[86:89], v[76:79], v[164:167], v[86:89]
	v_mfma_f32_16x16x32_bf16 v[90:93], v[216:219], v[168:171], v[90:93]
	v_mfma_f32_16x16x32_bf16 v[94:97], v[220:223], v[168:171], v[94:97]
	v_mfma_f32_16x16x32_bf16 v[98:101], v[242:245], v[168:171], v[98:101]
	v_mfma_f32_16x16x32_bf16 v[102:105], v[76:79], v[168:171], v[102:105]
	v_mfma_f32_16x16x32_bf16 v[106:109], v[216:219], v[174:177], v[106:109]
	v_mfma_f32_16x16x32_bf16 v[110:113], v[220:223], v[174:177], v[110:113]
	v_mfma_f32_16x16x32_bf16 v[114:117], v[242:245], v[174:177], v[114:117]
	v_mfma_f32_16x16x32_bf16 v[118:121], v[76:79], v[174:177], v[118:121]
	v_mfma_f32_16x16x32_bf16 v[122:125], v[216:219], v[182:185], v[122:125]
	v_mfma_f32_16x16x32_bf16 v[126:129], v[220:223], v[182:185], v[126:129]
	v_mfma_f32_16x16x32_bf16 v[136:139], v[242:245], v[182:185], v[136:139]
	v_mfma_f32_16x16x32_bf16 v[140:143], v[76:79], v[182:185], v[140:143]
	s_setprio 0
	s_waitcnt vmcnt(0)
	s_barrier
	ds_read_b128 v[148:151], v80 offset:0
	ds_read_b128 v[152:155], v80 offset:2048
	ds_read_b128 v[156:159], v80 offset:4096
	ds_read_b128 v[160:163], v80 offset:6144
	ds_read_b128 v[164:167], v81 offset:0
	ds_read_b128 v[168:171], v81 offset:2048
	ds_read_b128 v[174:177], v81 offset:4096
	ds_read_b128 v[182:185], v81 offset:6144
	ds_read_b128 v[188:191], v144 offset:49152
	ds_read_b128 v[192:195], v144 offset:51200
	ds_read_b128 v[208:211], v144 offset:53248
	ds_read_b128 v[212:215], v144 offset:55296
	ds_read_b128 v[216:219], v145 offset:49152
	ds_read_b128 v[220:223], v145 offset:51200
	ds_read_b128 v[242:245], v145 offset:53248
	ds_read_b128 v[76:79], v145 offset:55296
	s_setprio 1
	s_waitcnt lgkmcnt(4)
	v_mfma_f32_16x16x32_bf16 v[62:65], v[188:191], v[148:151], v[62:65]
	v_mfma_f32_16x16x32_bf16 v[54:57], v[192:195], v[148:151], v[54:57]
	v_mfma_f32_16x16x32_bf16 v[58:61], v[208:211], v[148:151], v[58:61]
	v_mfma_f32_16x16x32_bf16 v[50:53], v[212:215], v[148:151], v[50:53]
	v_mfma_f32_16x16x32_bf16 v[46:49], v[188:191], v[152:155], v[46:49]
	v_mfma_f32_16x16x32_bf16 v[38:41], v[192:195], v[152:155], v[38:41]
	v_mfma_f32_16x16x32_bf16 v[42:45], v[208:211], v[152:155], v[42:45]
	v_mfma_f32_16x16x32_bf16 v[34:37], v[212:215], v[152:155], v[34:37]
	v_mfma_f32_16x16x32_bf16 v[30:33], v[188:191], v[156:159], v[30:33]
	v_mfma_f32_16x16x32_bf16 v[22:25], v[192:195], v[156:159], v[22:25]
	v_mfma_f32_16x16x32_bf16 v[26:29], v[208:211], v[156:159], v[26:29]
	v_mfma_f32_16x16x32_bf16 v[18:21], v[212:215], v[156:159], v[18:21]
	v_mfma_f32_16x16x32_bf16 v[14:17], v[188:191], v[160:163], v[14:17]
	v_mfma_f32_16x16x32_bf16 v[6:9], v[192:195], v[160:163], v[6:9]
	v_mfma_f32_16x16x32_bf16 v[10:13], v[208:211], v[160:163], v[10:13]
	v_mfma_f32_16x16x32_bf16 v[2:5], v[212:215], v[160:163], v[2:5]
	s_waitcnt lgkmcnt(0)
	v_mfma_f32_16x16x32_bf16 v[62:65], v[216:219], v[164:167], v[62:65]
	v_mfma_f32_16x16x32_bf16 v[54:57], v[220:223], v[164:167], v[54:57]
	v_mfma_f32_16x16x32_bf16 v[58:61], v[242:245], v[164:167], v[58:61]
	v_mfma_f32_16x16x32_bf16 v[50:53], v[76:79], v[164:167], v[50:53]
	v_mfma_f32_16x16x32_bf16 v[46:49], v[216:219], v[168:171], v[46:49]
	v_mfma_f32_16x16x32_bf16 v[38:41], v[220:223], v[168:171], v[38:41]
	v_mfma_f32_16x16x32_bf16 v[42:45], v[242:245], v[168:171], v[42:45]
	v_mfma_f32_16x16x32_bf16 v[34:37], v[76:79], v[168:171], v[34:37]
	v_mfma_f32_16x16x32_bf16 v[30:33], v[216:219], v[174:177], v[30:33]
	v_mfma_f32_16x16x32_bf16 v[22:25], v[220:223], v[174:177], v[22:25]
	v_mfma_f32_16x16x32_bf16 v[26:29], v[242:245], v[174:177], v[26:29]
	v_mfma_f32_16x16x32_bf16 v[18:21], v[76:79], v[174:177], v[18:21]
	v_mfma_f32_16x16x32_bf16 v[14:17], v[216:219], v[182:185], v[14:17]
	v_mfma_f32_16x16x32_bf16 v[6:9], v[220:223], v[182:185], v[6:9]
	v_mfma_f32_16x16x32_bf16 v[10:13], v[242:245], v[182:185], v[10:13]
	v_mfma_f32_16x16x32_bf16 v[2:5], v[76:79], v[182:185], v[2:5]
	s_setprio 0
	ds_read_b128 v[148:151], v80 offset:16384
	ds_read_b128 v[152:155], v80 offset:18432
	ds_read_b128 v[156:159], v80 offset:20480
	ds_read_b128 v[160:163], v80 offset:22528
	ds_read_b128 v[164:167], v81 offset:16384
	ds_read_b128 v[168:171], v81 offset:18432
	ds_read_b128 v[174:177], v81 offset:20480
	ds_read_b128 v[182:185], v81 offset:22528
	s_setprio 1
	s_waitcnt lgkmcnt(4)
	v_mfma_f32_16x16x32_bf16 v[66:69], v[188:191], v[148:151], v[66:69]
	v_mfma_f32_16x16x32_bf16 v[70:73], v[192:195], v[148:151], v[70:73]
	v_mfma_f32_16x16x32_bf16 v[82:85], v[208:211], v[148:151], v[82:85]
	v_mfma_f32_16x16x32_bf16 v[86:89], v[212:215], v[148:151], v[86:89]
	v_mfma_f32_16x16x32_bf16 v[90:93], v[188:191], v[152:155], v[90:93]
	v_mfma_f32_16x16x32_bf16 v[94:97], v[192:195], v[152:155], v[94:97]
	v_mfma_f32_16x16x32_bf16 v[98:101], v[208:211], v[152:155], v[98:101]
	v_mfma_f32_16x16x32_bf16 v[102:105], v[212:215], v[152:155], v[102:105]
	v_mfma_f32_16x16x32_bf16 v[106:109], v[188:191], v[156:159], v[106:109]
	v_mfma_f32_16x16x32_bf16 v[110:113], v[192:195], v[156:159], v[110:113]
	v_mfma_f32_16x16x32_bf16 v[114:117], v[208:211], v[156:159], v[114:117]
	v_mfma_f32_16x16x32_bf16 v[118:121], v[212:215], v[156:159], v[118:121]
	v_mfma_f32_16x16x32_bf16 v[122:125], v[188:191], v[160:163], v[122:125]
	v_mfma_f32_16x16x32_bf16 v[126:129], v[192:195], v[160:163], v[126:129]
	v_mfma_f32_16x16x32_bf16 v[136:139], v[208:211], v[160:163], v[136:139]
	v_mfma_f32_16x16x32_bf16 v[140:143], v[212:215], v[160:163], v[140:143]
	s_waitcnt lgkmcnt(0)
	v_mfma_f32_16x16x32_bf16 v[66:69], v[216:219], v[164:167], v[66:69]
	v_mfma_f32_16x16x32_bf16 v[70:73], v[220:223], v[164:167], v[70:73]
	v_mfma_f32_16x16x32_bf16 v[82:85], v[242:245], v[164:167], v[82:85]
	v_mfma_f32_16x16x32_bf16 v[86:89], v[76:79], v[164:167], v[86:89]
	v_mfma_f32_16x16x32_bf16 v[90:93], v[216:219], v[168:171], v[90:93]
	v_mfma_f32_16x16x32_bf16 v[94:97], v[220:223], v[168:171], v[94:97]
	v_mfma_f32_16x16x32_bf16 v[98:101], v[242:245], v[168:171], v[98:101]
	v_mfma_f32_16x16x32_bf16 v[102:105], v[76:79], v[168:171], v[102:105]
	v_mfma_f32_16x16x32_bf16 v[106:109], v[216:219], v[174:177], v[106:109]
	v_mfma_f32_16x16x32_bf16 v[110:113], v[220:223], v[174:177], v[110:113]
	v_mfma_f32_16x16x32_bf16 v[114:117], v[242:245], v[174:177], v[114:117]
	v_mfma_f32_16x16x32_bf16 v[118:121], v[76:79], v[174:177], v[118:121]
	v_mfma_f32_16x16x32_bf16 v[122:125], v[216:219], v[182:185], v[122:125]
	v_mfma_f32_16x16x32_bf16 v[126:129], v[220:223], v[182:185], v[126:129]
	v_mfma_f32_16x16x32_bf16 v[136:139], v[242:245], v[182:185], v[136:139]
	v_mfma_f32_16x16x32_bf16 v[140:143], v[76:79], v[182:185], v[140:143]
	s_setprio 0
	s_nop 7
	s_nop 7
	s_nop 7
	s_add_i32 s48, s48, 1
	s_mov_b32 s39, 0
	v_readlane_b32 s30, v249, 0
	s_nop 0
	s_and_b32 s31, s30, 7
	s_lshr_b32 s30, s30, 3
	s_cmp_lt_u32 s30, 32
	s_cselect_b32 s35, 6, 5
	s_cmp_lt_u32 s48, s35
	s_cbranch_scc0 .Lf2_c1_extra
	s_lshl_b32 s33, s48, 6
	s_add_i32 s33, s33, s30
	s_cmp_ge_u32 s33, 0xb0
	s_cselect_b32 s34, 1, 0
	s_mul_i32 s36, s34, 0xb0
	s_sub_i32 s33, s33, s36
	s_lshr_b32 s37, s33, 2
	s_and_b32 s33, s33, 3
	s_lshl_b32 s34, s34, 3
	s_add_i32 s33, s33, s34
	s_lshl_b32 s33, s33, 3
	s_add_i32 s36, s33, s31
	s_add_i32 s38, s36, 32
	s_branch .Lf2_c1_have

.Lf2_c1_have:
	s_mov_b32 s39, 2
	s_lshl_b32 s30, s36, 18
	s_add_u32 s50, s6, s30
	s_addc_u32 s51, s7, 0
	s_lshl_b32 s30, s38, 18
	s_add_u32 s52, s6, s30
	s_addc_u32 s53, s7, 0
	s_lshl_b32 s30, s37, 18
	s_add_u32 s58, s19, s30
	s_addc_u32 s59, s20, 0
	s_barrier
	s_add_i32 m0, s64, 0x0
	s_nop 0
	global_load_lds_dwordx4 v199, s[50:51]
	s_add_u32 s50, s50, 0x10000
	s_addc_u32 s51, s51, 0
	s_add_i32 m0, s64, 0x1000
	s_nop 0
	global_load_lds_dwordx4 v199, s[50:51]
	s_add_u32 s50, s50, 0x10000
	s_addc_u32 s51, s51, 0
	s_add_i32 m0, s64, 0x2000
	s_nop 0
	global_load_lds_dwordx4 v199, s[50:51]
	s_add_u32 s50, s50, 0x10000
	s_addc_u32 s51, s51, 0
	s_add_i32 m0, s64, 0x3000
	s_nop 0
	global_load_lds_dwordx4 v199, s[50:51]
	s_sub_u32 s50, s50, 0x2ff80
	s_subb_u32 s51, s51, 0
	s_add_i32 m0, s64, 0x4000
	s_nop 0
	global_load_lds_dwordx4 v199, s[52:53]
	s_add_u32 s52, s52, 0x10000
	s_addc_u32 s53, s53, 0
	s_add_i32 m0, s64, 0x5000
	s_nop 0
	global_load_lds_dwordx4 v199, s[52:53]
	s_add_u32 s52, s52, 0x10000
	s_addc_u32 s53, s53, 0
	s_add_i32 m0, s64, 0x6000
	s_nop 0
	global_load_lds_dwordx4 v199, s[52:53]
	s_add_u32 s52, s52, 0x10000
	s_addc_u32 s53, s53, 0
	s_add_i32 m0, s64, 0x7000
	s_nop 0
	global_load_lds_dwordx4 v199, s[52:53]
	s_sub_u32 s52, s52, 0x2ff80
	s_subb_u32 s53, s53, 0
	s_add_i32 m0, s64, 0x8000
	s_nop 0
	global_load_lds_dwordx4 v199, s[58:59]
	s_add_u32 s58, s58, 0x10000
	s_addc_u32 s59, s59, 0
	s_add_i32 m0, s64, 0x9000
	s_nop 0
	global_load_lds_dwordx4 v199, s[58:59]
	s_add_u32 s58, s58, 0x10000
	s_addc_u32 s59, s59, 0
	s_add_i32 m0, s64, 0xa000
	s_nop 0
	global_load_lds_dwordx4 v199, s[58:59]
	s_add_u32 s58, s58, 0x10000
	s_addc_u32 s59, s59, 0
	s_add_i32 m0, s64, 0xb000
	s_nop 0
	global_load_lds_dwordx4 v199, s[58:59]
	s_sub_u32 s58, s58, 0x2ff80
	s_subb_u32 s59, s59, 0
